# sample-attn P.C part: all LDS fragment reads issued up front with counted lgkmcnt; no vmcnt(0) before tr reads; page-id load waited later
# speedup vs baseline: 1.0025x; 1.0025x over previous
.LBB0_1863:
	s_add_i32 s46, s78, 2
	s_min_i32 s80, s46, s63
	s_ashr_i32 s46, s80, 3
	s_mul_i32 s46, s46, s24
	s_add_i32 s46, s46, s25
	s_lshl_b32 s46, s46, 2
	s_bfe_u32 s48, s80, 0x20001
	s_or_b32 s48, s46, s48
	s_ashr_i32 s49, s48, 31
	s_and_b32 s47, s78, 7
	s_lshl_b64 s[48:49], s[48:49], 2
	s_add_u32 s48, s18, s48
	s_addc_u32 s49, s19, s49
	s_load_dword s46, s[48:49], 0x0
	s_cmp_lg_u32 s47, 0
	v_mov_b32_e32 v212, v148
	v_mov_b32_e32 v213, v146
	s_cbranch_scc1 .LBB0_1865
	v_mov_b32_e32 v212, 0
	v_mov_b32_e32 v213, 0xf149f2ca
	v_mov_b32_e32 v138, 0
	v_mov_b32_e32 v139, v212
	v_mov_b32_e32 v140, v212
	v_mov_b32_e32 v141, v212
	v_mov_b32_e32 v130, 0
	v_mov_b32_e32 v131, v212
	v_mov_b32_e32 v132, v212
	v_mov_b32_e32 v133, v212
	v_mov_b32_e32 v142, 0
	v_mov_b32_e32 v143, v212
	v_mov_b32_e32 v144, v212
	v_mov_b32_e32 v145, v212
	v_mov_b32_e32 v134, 0
	v_mov_b32_e32 v135, v212
	v_mov_b32_e32 v136, v212
	v_mov_b32_e32 v137, v212

.LBB0_1869:
	s_waitcnt lgkmcnt(0)
	ds_read2_b32 v[150:151], v208 offset0:32 offset1:48
	ds_read2_b32 v[148:149], v208 offset1:16
	s_waitcnt lgkmcnt(0)
	v_max_f32_e32 v146, v151, v151
	v_max_f32_e32 v147, v150, v150
	v_max_f32_e32 v146, v147, v146
	v_max3_f32 v146, v148, v149, v146
	s_nop 1
	v_mov_b32_dpp v147, v146 quad_perm:[1,0,3,2] row_mask:0xf bank_mask:0xf bound_ctrl:1
	v_max_f32_e32 v147, v147, v147
	v_max_f32_e32 v146, v146, v147
	s_nop 1
	v_mov_b32_dpp v147, v146 quad_perm:[2,3,0,1] row_mask:0xf bank_mask:0xf bound_ctrl:1
	v_max_f32_e32 v147, v147, v147
	v_max_f32_e32 v146, v146, v147
	s_nop 1
	v_mov_b32_dpp v147, v146 row_half_mirror row_mask:0xf bank_mask:0xf bound_ctrl:1
	v_max_f32_e32 v147, v147, v147
	v_max_f32_e32 v146, v146, v147
	s_nop 1
	v_mov_b32_dpp v147, v146 row_mirror row_mask:0xf bank_mask:0xf bound_ctrl:1
	v_max3_f32 v146, v213, v146, v147
	v_sub_f32_e32 v147, v148, v146
	v_exp_f32_e32 v147, v147
	v_sub_f32_e32 v148, v149, v146
	v_exp_f32_e32 v148, v148
	v_sub_f32_e32 v149, v150, v146
	v_bfe_u32 v150, v147, 16, 1
	v_exp_f32_e32 v149, v149
	v_add3_u32 v150, v147, v150, s74
	ds_write_b16_d16_hi v209, v150
	v_bfe_u32 v150, v148, 16, 1
	v_add3_u32 v150, v148, v150, s74
	ds_write_b16_d16_hi v209, v150 offset:32
	v_sub_f32_e32 v150, v151, v146
	v_bfe_u32 v153, v149, 16, 1
	v_exp_f32_e32 v150, v150
	v_sub_f32_e32 v152, v213, v146
	v_add3_u32 v151, v149, v153, s74
	ds_write_b16_d16_hi v209, v151 offset:64
	v_exp_f32_e32 v151, v152
	v_bfe_u32 v152, v150, 16, 1
	v_add3_u32 v152, v150, v152, s74
	ds_write_b16_d16_hi v209, v152 offset:96
	s_and_saveexec_b64 s[48:49], s[8:9]
	ds_write_b32 v210, v151
	s_or_b64 exec, exec, s[48:49]
	v_add_f32_e32 v147, 0, v147
	v_add_f32_e32 v147, v148, v147
	v_add_f32_e32 v147, v149, v147
	v_add_f32_e32 v148, v150, v147
	s_waitcnt lgkmcnt(0)
	v_add_u32_e32 v147, 0, v184
	s_barrier
	v_add_u32_e32 v147, 0x1cb00, v147
	v_fmac_f32_e32 v148, v212, v151
	ds_read_b128 v[150:153], v147
	ds_read_b128 v[154:157], v147 offset:64
	ds_read_b128 v[214:217], v211
	ds_read_b128 v[218:221], v211 offset:2304
	ds_read_b64_tr_b16 v[198:199], v186 offset:2112
	ds_read_b64_tr_b16 v[196:197], v186
	ds_read_b64_tr_b16 v[200:201], v186 offset:32
	ds_read_b64_tr_b16 v[202:203], v186 offset:2144
	ds_read_b128 v[222:225], v211 offset:64
	ds_read_b128 v[238:241], v211 offset:2368
	ds_read_b64_tr_b16 v[242:243], v186 offset:16896
	ds_read_b64_tr_b16 v[244:245], v186 offset:19008
	s_lshr_b32 s81, s78, 3
	s_cmp_lg_u32 s47, 7
	s_cselect_b64 s[48:49], -1, 0
	s_and_b64 vcc, exec, s[48:49]
	s_waitcnt lgkmcnt(11)
	v_pk_mul_f32 v[134:135], v[134:135], v[150:151]
	v_pk_mul_f32 v[136:137], v[136:137], v[152:153]
	v_pk_mul_f32 v[142:143], v[142:143], v[150:151]
	v_pk_mul_f32 v[144:145], v[144:145], v[152:153]
	ds_read_b64_tr_b16 v[150:151], v186 offset:16928
	ds_read_b64_tr_b16 v[152:153], v186 offset:19040
	s_waitcnt lgkmcnt(12)
	v_pk_mul_f32 v[130:131], v[130:131], v[154:155]
	v_pk_mul_f32 v[132:133], v[132:133], v[156:157]
	v_pk_mul_f32 v[138:139], v[138:139], v[154:155]
	v_pk_mul_f32 v[140:141], v[140:141], v[156:157]
	s_waitcnt lgkmcnt(8)
	v_mfma_f32_16x16x32_bf16 v[134:137], v[214:217], v[196:199], v[134:137]
	v_mfma_f32_16x16x32_bf16 v[130:133], v[218:221], v[196:199], v[130:133]
	s_waitcnt lgkmcnt(6)
	v_mfma_f32_16x16x32_bf16 v[142:145], v[214:217], v[200:203], v[142:145]
	v_mfma_f32_16x16x32_bf16 v[138:141], v[218:221], v[200:203], v[138:141]
	s_waitcnt lgkmcnt(2)
	v_mfma_f32_16x16x32_bf16 v[134:137], v[222:225], v[242:245], v[134:137]
	v_mfma_f32_16x16x32_bf16 v[130:133], v[238:241], v[242:245], v[130:133]
	s_waitcnt lgkmcnt(0)
	v_mfma_f32_16x16x32_bf16 v[142:145], v[222:225], v[150:153], v[142:145]
	v_mfma_f32_16x16x32_bf16 v[138:141], v[238:241], v[150:153], v[138:141]
	s_cbranch_vccnz .LBB0_1875
	s_mul_i32 s47, s81, s24
	s_add_i32 s50, s47, s25
	s_ashr_i32 s51, s50, 31
	s_lshl_b64 s[52:53], s[50:51], 15
	v_mov_b32_e32 v151, s53
	v_or_b32_e32 v150, s52, v168
	v_lshl_add_u64 v[152:153], v[162:163], 0, v[150:151]
	global_store_dword v[152:153], v134, off
	global_store_dword v[152:153], v135, off offset:1024
	global_store_dword v[152:153], v136, off offset:2048
	global_store_dword v[152:153], v137, off offset:3072
	global_store_dword v[152:153], v142, off offset:64
	global_store_dword v[152:153], v143, off offset:1088
	global_store_dword v[152:153], v144, off offset:2112
	global_store_dword v[152:153], v145, off offset:3136
	v_or_b32_e32 v152, 0x4000, v150
	v_mov_b32_e32 v153, s53
	v_lshl_add_u64 v[154:155], v[162:163], 0, v[152:153]
	global_store_dword v[154:155], v130, off
	v_or_b32_e32 v154, 0x4400, v150
	v_mov_b32_e32 v155, s53
	v_lshl_add_u64 v[156:157], v[162:163], 0, v[154:155]
	v_add_f32_dpp v147, v148, v148 quad_perm:[1,0,3,2] row_mask:0xf bank_mask:0xf bound_ctrl:1
	global_store_dword v[156:157], v131, off
	v_or_b32_e32 v156, 0x4800, v150
	v_mov_b32_e32 v157, s53
	v_lshl_add_u64 v[152:153], v[164:165], 0, v[152:153]
	v_add_f32_dpp v147, v147, v147 quad_perm:[2,3,0,1] row_mask:0xf bank_mask:0xf bound_ctrl:1
	v_lshl_add_u64 v[196:197], v[162:163], 0, v[156:157]
	v_or_b32_e32 v150, 0x4c00, v150
	global_store_dword v[152:153], v138, off
	v_lshl_add_u64 v[152:153], v[164:165], 0, v[154:155]
	v_add_f32_dpp v147, v147, v147 row_half_mirror row_mask:0xf bank_mask:0xf bound_ctrl:1
	global_store_dword v[196:197], v132, off
	v_lshl_add_u64 v[196:197], v[162:163], 0, v[150:151]
	global_store_dword v[152:153], v139, off
	v_lshl_add_u64 v[152:153], v[164:165], 0, v[156:157]
	v_lshl_add_u64 v[150:151], v[164:165], 0, v[150:151]
	v_mov_b32_dpp v149, v147 row_mirror row_mask:0xf bank_mask:0xf bound_ctrl:1
	global_store_dword v[196:197], v133, off
	global_store_dword v[152:153], v140, off
	global_store_dword v[150:151], v141, off
	s_and_saveexec_b64 s[52:53], s[8:9]
	s_cbranch_execz .LBB0_1874
	s_lshl_b64 s[50:51], s[50:51], 8
	v_lshl_add_u64 v[150:151], v[166:167], 0, s[50:51]
	v_add_f32_e32 v147, v147, v149
	global_store_dwordx2 v[150:151], v[146:147], off
